# v16: v15 + online-softmax max reduction split into two interleaved dependency chains (p0 / p1 halves)
# baseline (speedup 1.0000x reference)
.LBB0_526:
	ds_read_b128 v[64:67], v192 offset:49152
	ds_read_b128 v[68:71], v192 offset:57344
	ds_read_b128 v[232:235], v200 offset:49152
	ds_read_b128 v[236:239], v200 offset:57344
	ds_read_b128 v[250:253], v199 offset:49152
	ds_read_b128 v[244:247], v199 offset:57344
	ds_read_b128 v[212:215], v198 offset:49152
	ds_read_b128 v[216:219], v198 offset:57344
	v_add_f32_e32 v162, v163, v177
	s_waitcnt lgkmcnt(6)
	v_mfma_f32_32x32x16_bf16 v[80:95], v[64:67], v[118:121], 0
	v_add_f32_e32 v162, v164, v162
	v_add_f32_e32 v162, v207, v162
	v_add_f32_e32 v162, v176, v162
	v_add_f32_e32 v162, v210, v162
	v_mfma_f32_32x32x16_bf16 v[64:79], v[68:71], v[118:121], 0
	v_add_f32_e32 v162, v165, v162
	v_add_f32_e32 v162, v175, v162
	v_add_f32_e32 v162, v166, v162
	v_add_f32_e32 v162, v173, v162
	v_add_f32_e32 v162, v167, v162
	s_waitcnt lgkmcnt(4)
	v_mfma_f32_32x32x16_bf16 v[80:95], v[232:235], v[114:117], v[80:95]
	ds_read_b128 v[232:235], v195 offset:49152
	v_add_f32_e32 v162, v174, v162
	v_exp_f32_e32 v160, v160
	v_add_f32_e32 v162, v168, v162
	v_exp_f32_e32 v161, v161
	v_mfma_f32_32x32x16_bf16 v[64:79], v[236:239], v[114:117], v[64:79]
	ds_read_b128 v[236:239], v195 offset:57344
	v_add_f32_e32 v162, v171, v162
	v_exp_f32_e32 v158, v158
	v_add_f32_e32 v162, v169, v162
	v_exp_f32_e32 v159, v159
	s_waitcnt lgkmcnt(4)
	v_mfma_f32_32x32x16_bf16 v[80:95], v[250:253], v[126:129], v[80:95]
	ds_read_b128 v[250:253], v193 offset:49152
	v_add_f32_e32 v162, v172, v162
	v_exp_f32_e32 v154, v154
	v_add_f32_e32 v162, v160, v162
	v_exp_f32_e32 v155, v155
	v_mfma_f32_32x32x16_bf16 v[64:79], v[244:247], v[126:129], v[64:79]
	ds_read_b128 v[244:247], v193 offset:57344
	v_add_f32_e32 v162, v161, v162
	v_exp_f32_e32 v150, v150
	v_add_f32_e32 v162, v158, v162
	v_exp_f32_e32 v151, v151
	s_waitcnt lgkmcnt(4)
	v_mfma_f32_32x32x16_bf16 v[80:95], v[212:215], v[122:125], v[80:95]
	ds_read_b128 v[212:215], v202 offset:49152
	v_add_f32_e32 v162, v159, v162
	v_exp_f32_e32 v148, v148
	v_add_f32_e32 v162, v154, v162
	v_exp_f32_e32 v149, v149
	v_mfma_f32_32x32x16_bf16 v[64:79], v[216:219], v[122:125], v[64:79]
	ds_read_b128 v[216:219], v202 offset:57344
	v_add_f32_e32 v162, v155, v162
	v_exp_f32_e32 v156, v156
	v_add_f32_e32 v162, v150, v162
	v_exp_f32_e32 v157, v157
	s_waitcnt lgkmcnt(4)
	v_mfma_f32_32x32x16_bf16 v[80:95], v[232:235], v[110:113], v[80:95]
	ds_read_b128 v[232:235], v201 offset:49152
	v_add_f32_e32 v162, v151, v162
	v_exp_f32_e32 v152, v152
	v_add_f32_e32 v162, v148, v162
	v_exp_f32_e32 v153, v153
	v_mfma_f32_32x32x16_bf16 v[64:79], v[236:239], v[110:113], v[64:79]
	ds_read_b128 v[236:239], v201 offset:57344
	v_add_f32_e32 v162, v149, v162
	v_exp_f32_e32 v146, v146
	v_add_f32_e32 v162, v156, v162
	v_exp_f32_e32 v147, v147
	s_waitcnt lgkmcnt(4)
	v_mfma_f32_32x32x16_bf16 v[80:95], v[250:253], v[106:109], v[80:95]
	v_add_f32_e32 v162, v157, v162
	v_add_f32_e32 v162, v152, v162
	v_add_f32_e32 v162, v153, v162
	v_add_f32_e32 v162, v146, v162
	v_add_f32_e32 v204, v147, v162
	v_mov_b32_e32 v205, v204
	v_mfma_f32_32x32x16_bf16 v[64:79], v[244:247], v[106:109], v[64:79]
	s_nop 0
	v_permlane32_swap_b32_e32 v204, v205
	v_cvt_pk_bf16_f32 v162, v163, v177
	v_cvt_pk_bf16_f32 v163, v164, v207
	v_cvt_pk_bf16_f32 v164, v176, v210
	s_waitcnt lgkmcnt(2)
	v_mfma_f32_32x32x16_bf16 v[80:95], v[212:215], v[102:105], v[80:95]
	v_cvt_pk_bf16_f32 v165, v165, v175
	v_cvt_pk_bf16_f32 v166, v166, v173
	v_cvt_pk_bf16_f32 v167, v167, v174
	v_cvt_pk_bf16_f32 v168, v168, v171
	v_mfma_f32_32x32x16_bf16 v[64:79], v[216:219], v[102:105], v[64:79]
	v_cvt_pk_bf16_f32 v169, v169, v172
	v_cvt_pk_bf16_f32 v172, v160, v161
	v_cvt_pk_bf16_f32 v173, v158, v159
	v_cvt_pk_bf16_f32 v174, v154, v155
	ds_read_b64_tr_b16 v[210:211], v187 offset:0x0
	ds_read_b64_tr_b16 v[212:213], v187 offset:0x800
	ds_read_b64_tr_b16 v[214:215], v187 offset:0x200
	ds_read_b64_tr_b16 v[216:217], v187 offset:0xa00
	ds_read_b64_tr_b16 v[218:219], v187 offset:0x400
	ds_read_b64_tr_b16 v[220:221], v187 offset:0xc00
	ds_read_b64_tr_b16 v[222:223], v187 offset:0x600
	ds_read_b64_tr_b16 v[224:225], v187 offset:0xe00
	s_waitcnt lgkmcnt(8)
	v_mfma_f32_32x32x16_bf16 v[80:95], v[232:235], v[98:101], v[80:95]
	v_cvt_pk_bf16_f32 v175, v150, v151
	v_cvt_pk_bf16_f32 v206, v148, v149
	v_cvt_pk_bf16_f32 v207, v156, v157
	v_mfma_f32_32x32x16_bf16 v[64:79], v[236:239], v[98:101], v[64:79]
	v_cvt_pk_bf16_f32 v208, v152, v153
	v_cvt_pk_bf16_f32 v209, v146, v147
	s_waitcnt vmcnt(0)
	ds_write_b128 v188, v[134:137] offset:32768
	ds_write_b128 v189, v[142:145] offset:32768
	global_load_dwordx4 v[146:149], v178, s[66:67]
	global_load_dwordx4 v[150:153], v179, s[66:67]
	global_load_dwordx4 v[154:157], v178, s[98:99]
	global_load_dwordx4 v[158:161], v179, s[98:99]
	s_add_u32 s66, s66, 0x4000
	s_addc_u32 s67, s67, 0
	s_add_u32 s98, s98, 0x4000
	s_addc_u32 s99, s99, 0
	s_waitcnt lgkmcnt(6)
	v_mfma_f32_32x32x16_bf16 v[0:15], v[162:165], v[210:213], v[0:15]
	ds_read_b64_tr_b16 v[210:211], v187 offset:0x1000
	ds_read_b64_tr_b16 v[212:213], v187 offset:0x1800
	v_max_f32_e32 v240, v80, v81
	v_max_f32_e32 v241, v64, v65
	v_max3_f32 v240, v240, v82, v83
	v_max3_f32 v241, v241, v66, v67
	v_max3_f32 v240, v240, v84, v85
	v_max3_f32 v241, v241, v68, v69
	v_mfma_f32_32x32x16_bf16 v[48:63], v[162:165], v[214:217], v[48:63]
	ds_read_b64_tr_b16 v[214:215], v187 offset:0x1200
	ds_read_b64_tr_b16 v[216:217], v187 offset:0x1a00
	v_max3_f32 v240, v240, v86, v87
	v_max3_f32 v241, v241, v70, v71
	v_max3_f32 v240, v240, v88, v89
	v_max3_f32 v241, v241, v72, v73
	v_max3_f32 v240, v240, v90, v91
	v_max3_f32 v241, v241, v74, v75
	s_waitcnt lgkmcnt(6)
	v_mfma_f32_32x32x16_bf16 v[32:47], v[162:165], v[218:221], v[32:47]
	ds_read_b64_tr_b16 v[218:219], v187 offset:0x1400
	ds_read_b64_tr_b16 v[220:221], v187 offset:0x1c00
	v_max3_f32 v240, v240, v92, v93
	v_max3_f32 v241, v241, v76, v77
	v_max3_f32 v240, v240, v94, v95
	v_max3_f32 v241, v241, v78, v79
	v_max_f32_e32 v240, v240, v241
	v_mfma_f32_32x32x16_bf16 v[16:31], v[162:165], v[222:225], v[16:31]
	ds_read_b64_tr_b16 v[222:223], v187 offset:0x1600
	ds_read_b64_tr_b16 v[224:225], v187 offset:0x1e00
	v_mov_b32_e32 v241, v240
	s_nop 1
	v_permlane32_swap_b32_e32 v240, v241
	v_max_f32_e32 v240, v240, v241
	v_sub_f32_e32 v241, v240, v243
	v_cmp_ge_f32_e32 vcc, s92, v241
	s_waitcnt lgkmcnt(4)
	v_mfma_f32_32x32x16_bf16 v[0:15], v[166:169], v[210:213], v[0:15]
	ds_read_b64_tr_b16 v[210:211], v187 offset:0x2000
	ds_read_b64_tr_b16 v[212:213], v187 offset:0x2800
	s_cmp_eq_u64 vcc, exec
	s_cselect_b64 s[42:43], -1, 0
	s_cbranch_scc1 .Lattn_common_a
	v_max_f32_e32 v240, v243, v240
	v_sub_f32_e32 v241, v243, v240
	v_mul_f32_e32 v241, 0x3e0293ee, v241
	v_exp_f32_e32 v241, v241
	v_mov_b32_e32 v243, v240
	v_mul_f32_e32 v242, 0xbe0293ee, v243

.LBB0_532:
	s_waitcnt lgkmcnt(6)
	v_mfma_f32_32x32x16_bf16 v[0:15], v[162:165], v[210:213], v[0:15]
	ds_read_b64_tr_b16 v[210:211], v186 offset:0x1000
	ds_read_b64_tr_b16 v[212:213], v186 offset:0x1800
	v_max_f32_e32 v240, v80, v81
	v_max_f32_e32 v241, v64, v65
	v_max3_f32 v240, v240, v82, v83
	v_max3_f32 v241, v241, v66, v67
	v_max3_f32 v240, v240, v84, v85
	v_max3_f32 v241, v241, v68, v69
	v_mfma_f32_32x32x16_bf16 v[48:63], v[162:165], v[214:217], v[48:63]
	ds_read_b64_tr_b16 v[214:215], v186 offset:0x1200
	ds_read_b64_tr_b16 v[216:217], v186 offset:0x1a00
	v_max3_f32 v240, v240, v86, v87
	v_max3_f32 v241, v241, v70, v71
	v_max3_f32 v240, v240, v88, v89
	v_max3_f32 v241, v241, v72, v73
	v_max3_f32 v240, v240, v90, v91
	v_max3_f32 v241, v241, v74, v75
	s_waitcnt lgkmcnt(6)
	v_mfma_f32_32x32x16_bf16 v[32:47], v[162:165], v[218:221], v[32:47]
	ds_read_b64_tr_b16 v[218:219], v186 offset:0x1400
	ds_read_b64_tr_b16 v[220:221], v186 offset:0x1c00
	v_max3_f32 v240, v240, v92, v93
	v_max3_f32 v241, v241, v76, v77
	v_max3_f32 v240, v240, v94, v95
	v_max3_f32 v241, v241, v78, v79
	v_max_f32_e32 v240, v240, v241
	v_mfma_f32_32x32x16_bf16 v[16:31], v[162:165], v[222:225], v[16:31]
	ds_read_b64_tr_b16 v[222:223], v186 offset:0x1600
	ds_read_b64_tr_b16 v[224:225], v186 offset:0x1e00
	v_mov_b32_e32 v241, v240
	s_nop 1
	v_permlane32_swap_b32_e32 v240, v241
	v_max_f32_e32 v240, v240, v241
	v_sub_f32_e32 v241, v240, v243
	v_cmp_ge_f32_e32 vcc, s92, v241
	s_waitcnt lgkmcnt(4)
	v_mfma_f32_32x32x16_bf16 v[0:15], v[166:169], v[210:213], v[0:15]
	ds_read_b64_tr_b16 v[210:211], v186 offset:0x2000
	ds_read_b64_tr_b16 v[212:213], v186 offset:0x2800
	s_cmp_eq_u64 vcc, exec
	s_cselect_b64 s[42:43], -1, 0
	s_cbranch_scc1 .Lattn_common_b
	v_max_f32_e32 v240, v243, v240
	v_sub_f32_e32 v241, v243, v240
	v_mul_f32_e32 v241, 0x3e0293ee, v241
	v_exp_f32_e32 v241, v241
	v_mov_b32_e32 v243, v240
	v_mul_f32_e32 v242, 0xbe0293ee, v243
